# phase-3 latent rmsnorm rows moved from the 192 tile-owning workgroups to the 320 idle ones (same per-row math)
# speedup vs baseline: 1.0026x; 1.0026x over previous
.LBB0_1574:
	v_readlane_b32 s0, v251, 47
	s_nop 1
	v_add_u32_e32 v2, s0, v184
	v_readlane_b32 s26, v254, 23
	s_cmpk_lg_i32 s90, 0x200
	s_cbranch_scc1 .Lln_std
	v_readlane_b32 s27, v251, 24
	s_nop 1
	s_sub_i32 s27, s27, 192
	s_cmp_lt_i32 s27, 0
	s_cbranch_scc1 .Lln_busy
	s_lshl_b32 s28, s27, 2
	s_movk_i32 s26, 0x500
	v_add_u32_e32 v2, s28, v184
	s_branch .Lln_std
.Lln_busy:
	v_mov_b32_e32 v2, 0x7fffffff
.Lln_std:
	v_cmp_gt_i32_e32 vcc, s25, v2
	s_and_saveexec_b64 s[12:13], vcc
	v_readlane_b32 s96, v254, 21
	v_readlane_b32 s97, v254, 22
	s_mov_b32 s2, s26
	v_readlane_b32 s3, v254, 24
	s_cbranch_execz .LBB0_1583
	v_and_b32_e32 v1, 64, v194
	v_add_u32_e32 v3, 64, v1
	v_xor_b32_e32 v1, 32, v194
	v_cmp_lt_i32_e32 vcc, v1, v3
	v_xor_b32_e32 v4, 16, v194
	v_and_b32_e32 v0, 63, v163
	v_cndmask_b32_e32 v1, v194, v1, vcc
	v_cmp_lt_i32_e32 vcc, v4, v3
	v_readlane_b32 s0, v254, 30
	v_lshlrev_b32_e32 v0, 2, v0
	v_cndmask_b32_e32 v4, v194, v4, vcc
	v_lshlrev_b32_e32 v16, 2, v4
	v_xor_b32_e32 v4, 8, v194
	v_cmp_lt_i32_e32 vcc, v4, v3
	s_lshl_b32 s14, s0, 8
	s_mov_b32 s15, s77
	v_cndmask_b32_e32 v4, v194, v4, vcc
	v_lshlrev_b32_e32 v17, 2, v4
	v_xor_b32_e32 v4, 4, v194
	v_cmp_lt_i32_e32 vcc, v4, v3
	v_lshlrev_b32_e32 v1, 2, v1
	s_mov_b64 s[18:19], 0
	v_cndmask_b32_e32 v4, v194, v4, vcc
	v_lshlrev_b32_e32 v18, 2, v4
	v_xor_b32_e32 v4, 2, v194
	v_cmp_lt_i32_e32 vcc, v4, v3
	v_readlane_b32 s1, v254, 31
	s_nop 0
	v_cndmask_b32_e32 v4, v194, v4, vcc
	v_lshlrev_b32_e32 v19, 2, v4
	v_xor_b32_e32 v4, 1, v194
	v_cmp_lt_i32_e32 vcc, v4, v3
	s_nop 1
	v_cndmask_b32_e32 v3, v194, v4, vcc
	v_lshlrev_b32_e32 v20, 2, v3
	s_branch .LBB0_1577
.LBB0_1576:
	s_or_b64 exec, exec, s[0:1]
	s_mov_b32 s2, s26
	s_movk_i32 s0, 0x7fff
	v_readlane_b32 s3, v254, 24
	v_add_u32_e32 v2, s2, v21
	v_cmp_lt_i32_e32 vcc, s0, v2
	s_or_b64 s[18:19], vcc, s[18:19]
	s_andn2_b64 exec, exec, s[18:19]
	s_cbranch_execz .LBB0_1583
